# hgC work queue: the next chunk id is drawn one iteration earlier (atomic issued mid-chunk, consumed at the next loop top) so its round trip is no longer exposed before the top-of-chunk barrier; on top
# baseline (speedup 1.0000x reference)
; DI void hg_phase_c(const P& p, const bf16_t* PROJ, const bf16_t* ST, bf16_t* Y, LAS unsigned char* L, unsigned* qcnt) {
;     ...
;     __syncthreads();
;     if (tid == 0) qs[0] = __hip_atomic_fetch_add(qcnt, 1u, __ATOMIC_RELAXED, __HIP_MEMORY_SCOPE_AGENT);
;     __syncthreads();
;     int ch = (int)qs[0], par = 0;
;     if (ch < 2048) { hg_raw_load(PROJ, ch, 4096, roff, rf); hg_raw_load(PROJ, ch, 5120, roff, rv); hg_raw_load(PROJ, ch, 3072, roff, rq); }
;     while (ch < 2048) {
;         const int bh = ch >> 6, n = ch & 63, b = bh >> 3, hh = bh & 7;
;         if (tid == 0) qs[par ^ 1] = __hip_atomic_fetch_add(qcnt, 1u, __ATOMIC_RELAXED, __HIP_MEMORY_SCOPE_AGENT);
.LBB0_420:
	s_or_b64 exec, exec, s[8:9]
	s_waitcnt vmcnt(0)
	v_readfirstlane_b32 s8, v2
	s_nop 1
	v_add_u32_e32 v1, s8, v1
	s_add_i32 s8, 0, 0x220a0
	v_mov_b32_e32 v2, s8
	ds_write_b32 v2, v1
	v_mov_b32_e32 v214, 0
	v_mov_b32_e32 v213, 1
	global_atomic_add v213, v214, v213, s[60:61] sc0

; DI void hg_phase_c(const P& p, const bf16_t* PROJ, const bf16_t* ST, bf16_t* Y, LAS unsigned char* L, unsigned* qcnt) {
;     ...
;         if (tid == 0) qs[par ^ 1] = __hip_atomic_fetch_add(qcnt, 1u, __ATOMIC_RELAXED, __HIP_MEMORY_SCOPE_AGENT);
;         __syncthreads();
;         const int nxt = (int)qs[par ^ 1];
;         hg_raw_store(rawf, tid, rf); hg_raw_store(rawv, tid, rv); hg_raw_store(rawq, tid, rq);
.LBB0_424:
	s_xor_b32 s95, s95, 1
	s_and_saveexec_b64 s[50:51], s[4:5]
	s_cbranch_execz .LBB0_428
	s_lshl_b32 s62, s95, 2
	s_add_i32 s62, s62, 0
	s_add_i32 s62, s62, 0x220a0
	s_waitcnt vmcnt(0)
	v_mov_b32_e32 v1, s62
	ds_write_b32 v1, v213

; #define LAS __attribute__((address_space(3)))
; DI float bf2f(unsigned v) { return __uint_as_float(v << 16); }
; DI void hg_gates(const LAS unsigned char* rawf, const float* lbl, int part, int hh, int d, float (&G)[16], float (&kk)[16]) {
;     const float l0 = lbl[hh * 128 + d], l1 = lbl[1024 + hh * 128 + d]; const float lb = __builtin_amdgcn_rcpf(1.f + __expf(l1 - l0));
;     float run = 0.f;
; #pragma unroll
;     for (int i = 0; i < 16; ++i) {
;         const float fl = bf2f(*(const LAS bf16_t*)(rawf + (16 * part + i) * 272 + d * 2));
;         const float sig = __builtin_amdgcn_rcpf(1.f + __expf(-fl)); const float f = lb + (1.f - lb) * sig;
;         kk[i] = (1.f - lb) * (1.f - sig); run += __builtin_amdgcn_logf(f) * 0.69314718056f; G[i] = run;
;     }
; DI void hg_phase_c(const P& p, const bf16_t* PROJ, const bf16_t* ST, bf16_t* Y, LAS unsigned char* L, unsigned* qcnt) {
;     ...
;         const int dt = w & 3, tt = w >> 2;
;         bf16x8 stf[8];
;         { const bf16_t* STc = ST + (size_t)ch * 16384 + (32 * dt + r) * 128 + 8 * lh;
; #pragma unroll
;           for (int ks = 0; ks < 8; ++ks) stf[ks] = *(const bf16x8*)(STc + 16 * ks); }
;         const size_t trow = (size_t)b * SEQ + n * 64 + 32 * tt + r;
;         u32x2 ggv[4]; f32x4 ogv[4];
; #pragma unroll
;         for (int g4 = 0; g4 < 4; ++g4) { const int dv0 = 32 * dt + 8 * g4 + 4 * lh; ggv[g4] = *(const u32x2*)(PROJ + trow * PIN + 6144 + hh * 128 + dv0); ogv[g4] = *(const f32x4*)(p.hg_out_norm + hh * 128 + dv0); }
;         float G[16], kk[16];
;         hg_gates(rawf, p.lb_logits, part, hh, d, G, kk);
.LBB0_430:
	s_lshl_b32 s62, s76, 1
	s_and_b32 s80, s62, 0x380
	v_or_b32_e32 v0, s80, v172
	v_lshlrev_b32_e32 v0, 2, v0
	v_mov_b32_e32 v1, v155
	v_lshl_add_u64 v[2:3], s[52:53], 0, v[0:1]
	s_waitcnt lgkmcnt(0)
	s_barrier
	v_add_co_u32_e32 v0, vcc, s90, v2
	s_ashr_i32 s82, s76, 9
	s_nop 0
	v_addc_co_u32_e32 v1, vcc, 0, v3, vcc
	s_ashr_i32 s77, s76, 31
	s_lshl_b32 s62, s76, 6
	s_lshl_b64 s[76:77], s[76:77], 15
	s_ashr_i32 s83, s82, 31
	s_and_b32 s97, s62, 0xfc0
	v_lshl_add_u64 v[2:3], v[156:157], 0, s[76:77]
	s_lshl_b64 s[76:77], s[82:83], 12
	s_or_b32 s76, s76, s97
	v_mov_b64_e32 v[0:1], s[64:65]
	s_mov_b32 s81, s63
	s_lshl_b32 s62, s80, 1
	s_lshl_b32 s80, s80, 2
	v_lshl_add_u64 v[168:169], s[76:77], 0, v[158:159]
	ds_read_u16 v6, v183 offset:57344
	ds_read_u16 v7, v183 offset:57616
	ds_read_u16 v8, v183 offset:57888
	ds_read_u16 v9, v183 offset:58160
	ds_read_u16 v10, v183 offset:58432
	ds_read_u16 v12, v183 offset:58704
	ds_read_u16 v13, v183 offset:58976
	ds_read_u16 v14, v183 offset:59248
	global_load_dwordx4 v[116:119], v[2:3], off
	global_load_dwordx4 v[112:115], v[2:3], off offset:32
	global_load_dwordx4 v[108:111], v[2:3], off offset:64
	global_load_dwordx4 v[104:107], v[2:3], off offset:96
	global_load_dwordx4 v[100:103], v[2:3], off offset:128
	global_load_dwordx4 v[96:99], v[2:3], off offset:160
	global_load_dwordx4 v[92:95], v[2:3], off offset:192
	global_load_dwordx4 v[88:91], v[2:3], off offset:224
	v_lshl_add_u64 v[2:3], v[160:161], 0, s[80:81]
	v_mad_u64_u32 v[0:1], s[76:77], v168, s88, v[0:1]
	global_load_dwordx4 v[84:87], v[2:3], off
	global_load_dwordx4 v[80:83], v[2:3], off offset:32
	global_load_dwordx4 v[76:79], v[2:3], off offset:64
	global_load_dwordx4 v[72:75], v[2:3], off offset:96
	s_waitcnt lgkmcnt(7)
	v_lshlrev_b32_e32 v3, 16, v6
	v_mov_b32_e32 v2, v1
	v_mul_f32_e32 v1, 0xbfb8aa3b, v3
	v_mad_u64_u32 v[2:3], s[76:77], v169, s88, v[2:3]
	s_waitcnt lgkmcnt(6)
	v_lshlrev_b32_e32 v6, 16, v7
	s_waitcnt lgkmcnt(5)
	v_lshlrev_b32_e32 v7, 16, v8
	s_waitcnt lgkmcnt(4)
	v_lshlrev_b32_e32 v8, 16, v9
	v_exp_f32_e32 v9, v1
	v_mov_b32_e32 v1, v2
	v_lshl_add_u64 v[0:1], v[0:1], 0, s[62:63]
	s_mov_b64 s[78:79], 0x3000
	v_mul_f32_e32 v6, 0xbfb8aa3b, v6
	v_lshl_add_u64 v[0:1], v[0:1], 0, v[154:155]
	v_exp_f32_e32 v6, v6
	v_lshl_add_u64 v[2:3], v[0:1], 0, s[78:79]
	v_add_co_u32_e32 v0, vcc, s91, v0
	v_mul_f32_e32 v7, 0xbfb8aa3b, v7
	s_nop 0
	v_addc_co_u32_e32 v1, vcc, 0, v1, vcc
	v_mul_f32_e32 v8, 0xbfb8aa3b, v8
	v_exp_f32_e32 v7, v7
	global_load_dwordx2 v[170:171], v[0:1], off
	global_load_dwordx2 v[166:167], v[2:3], off offset:16
	global_load_dwordx2 v[164:165], v[2:3], off offset:32
	global_load_dwordx2 v[162:163], v[2:3], off offset:48
	v_exp_f32_e32 v15, v8
	v_add_f32_e32 v8, 1.0, v9
	v_add_f32_e32 v6, 1.0, v6
	v_rcp_f32_e32 v0, v8
	v_rcp_f32_e32 v1, v6
	v_add_f32_e32 v7, 1.0, v7
	ds_read_u16 v16, v183 offset:59520
	ds_read_u16 v17, v183 offset:59792
	ds_read_u16 v18, v183 offset:60064
	ds_read_u16 v19, v183 offset:60336
	ds_read_u16 v23, v183 offset:60608
	ds_read_u16 v26, v183 offset:60880
	ds_read_u16 v29, v183 offset:61152
	ds_read_u16 v32, v183 offset:61424
	v_sub_f32_e32 v3, 1.0, v0
	s_waitcnt lgkmcnt(7)
	v_lshlrev_b32_e32 v16, 16, v16
	v_mul_f32_e32 v16, 0xbfb8aa3b, v16
	v_exp_f32_e32 v16, v16
	s_andn2_b64 vcc, exec, s[66:67]
	s_waitcnt vmcnt(22)
	v_sub_f32_e32 v4, v211, v210
	s_and_saveexec_b64 s[98:99], s[4:5]
	s_cbranch_execz .Lhgc_q_skip
	v_mov_b32_e32 v213, 1
	global_atomic_add v213, v155, v213, s[60:61] sc0
.Lhgc_q_skip:
	s_or_b64 exec, exec, s[98:99]
	v_mul_f32_e32 v4, 0x3fb8aa3b, v4
	v_exp_f32_e32 v4, v4
	s_nop 0
	v_add_f32_e32 v2, 1.0, v4
	v_rcp_f32_e32 v22, v2
	v_rcp_f32_e32 v2, v7
	v_sub_f32_e32 v4, 1.0, v1
	v_sub_f32_e32 v31, 1.0, v22
	v_fma_f32 v0, v31, v0, v22
	v_fma_f32 v1, v31, v1, v22
	v_log_f32_e32 v0, v0
	v_log_f32_e32 v1, v1
	v_mul_f32_e32 v8, v31, v3
	v_fma_f32 v3, v31, v2, v22
	v_log_f32_e32 v3, v3
	v_fma_f32 v11, v0, s92, 0
	v_fmamk_f32 v9, v1, 0x3f317218, v11
	v_add_f32_e32 v0, 1.0, v15
	v_sub_f32_e32 v1, 1.0, v2
	v_lshlrev_b32_e32 v2, 16, v10
	v_rcp_f32_e32 v0, v0
	v_mul_f32_e32 v2, 0xbfb8aa3b, v2
	v_fmamk_f32 v7, v3, 0x3f317218, v9
	v_exp_f32_e32 v3, v2
	v_mul_f32_e32 v6, v31, v4
	v_mul_f32_e32 v4, v31, v1
	v_fma_f32 v1, v31, v0, v22
	v_sub_f32_e32 v0, 1.0, v0
	v_mul_f32_e32 v2, v31, v0
	v_log_f32_e32 v0, v1
	v_add_f32_e32 v1, 1.0, v3
	v_rcp_f32_e32 v1, v1
	v_lshlrev_b32_e32 v3, 16, v12
	v_mul_f32_e32 v3, 0xbfb8aa3b, v3
	v_exp_f32_e32 v3, v3
	v_fmamk_f32 v5, v0, 0x3f317218, v7
	v_fma_f32 v0, v31, v1, v22
	v_log_f32_e32 v0, v0
	v_add_f32_e32 v3, 1.0, v3
	v_rcp_f32_e32 v10, v3
	v_sub_f32_e32 v1, 1.0, v1
	v_fmamk_f32 v3, v0, 0x3f317218, v5
	v_lshlrev_b32_e32 v0, 16, v13
	v_mul_f32_e32 v0, 0xbfb8aa3b, v0
	v_exp_f32_e32 v13, v0
	v_fma_f32 v12, v31, v10, v22
	v_sub_f32_e32 v0, 1.0, v10
	v_log_f32_e32 v10, v12
	v_add_f32_e32 v12, 1.0, v13
	v_lshlrev_b32_e32 v13, 16, v14
	v_rcp_f32_e32 v12, v12
	v_mul_f32_e32 v13, 0xbfb8aa3b, v13
	v_exp_f32_e32 v14, v13
	v_fmamk_f32 v13, v10, 0x3f317218, v3
	v_fma_f32 v10, v31, v12, v22
	v_log_f32_e32 v15, v10
	v_add_f32_e32 v10, 1.0, v14
	v_rcp_f32_e32 v14, v10
	v_sub_f32_e32 v10, 1.0, v12
	v_fmamk_f32 v12, v15, 0x3f317218, v13
	v_mul_f32_e32 v1, v31, v1
	v_fma_f32 v15, v31, v14, v22
	v_sub_f32_e32 v14, 1.0, v14
	v_mul_f32_e32 v27, v31, v14
	v_log_f32_e32 v14, v15
	v_add_f32_e32 v15, 1.0, v16
	v_rcp_f32_e32 v15, v15
	s_waitcnt lgkmcnt(6)
	v_lshlrev_b32_e32 v16, 16, v17
	v_mul_f32_e32 v16, 0xbfb8aa3b, v16
	v_exp_f32_e32 v16, v16
	v_fmamk_f32 v30, v14, 0x3f317218, v12
	v_fma_f32 v14, v31, v15, v22
	v_sub_f32_e32 v15, 1.0, v15
	v_mul_f32_e32 v24, v31, v15
	s_waitcnt lgkmcnt(5)
; #define LAS __attribute__((address_space(3)))
; DI float bf2f(unsigned v) { return __uint_as_float(v << 16); }
; DI void hg_gates(const LAS unsigned char* rawf, const float* lbl, int part, int hh, int d, float (&G)[16], float (&kk)[16]) {
;     const float l0 = lbl[hh * 128 + d], l1 = lbl[1024 + hh * 128 + d]; const float lb = __builtin_amdgcn_rcpf(1.f + __expf(l1 - l0));
;     float run = 0.f;
; #pragma unroll
;     for (int i = 0; i < 16; ++i) {
;         const float fl = bf2f(*(const LAS bf16_t*)(rawf + (16 * part + i) * 272 + d * 2));
;         const float sig = __builtin_amdgcn_rcpf(1.f + __expf(-fl)); const float f = lb + (1.f - lb) * sig;
;         kk[i] = (1.f - lb) * (1.f - sig); run += __builtin_amdgcn_logf(f) * 0.69314718056f; G[i] = run;
;     }
; DI void hg_phase_c(const P& p, const bf16_t* PROJ, const bf16_t* ST, bf16_t* Y, LAS unsigned char* L, unsigned* qcnt) {
;     ...
;         float G[16], kk[16];
;         hg_gates(rawf, p.lb_logits, part, hh, d, G, kk);
;         psum[part * 128 + d] = G[15];
;         { u32x4 a, c; hg_col16(rawv, part, d, a, c);
;           u32x2 t2; t2.x = a.x; t2.y = a.y; *(LAS u32x2*)(vT + d * 136 + part * 32) = t2; t2.x = a.z; t2.y = a.w; *(LAS u32x2*)(vT + d * 136 + part * 32 + 8) = t2;
;           t2.x = c.x; t2.y = c.y; *(LAS u32x2*)(vT + d * 136 + part * 32 + 16) = t2; t2.x = c.z; t2.y = c.w; *(LAS u32x2*)(vT + d * 136 + part * 32 + 24) = t2; }
;         float qs[16];
; #pragma unroll
;         for (int i = 0; i < 16; ++i) { const float ql = bf2f(*(const LAS bf16_t*)(rawq + (16 * part + i) * 272 + d * 2)); qs[i] = ql * __builtin_amdgcn_rcpf(1.f + __expf(-ql)); }
;         __syncthreads();
	v_lshlrev_b32_e32 v15, 16, v18
	v_add_f32_e32 v16, 1.0, v16
	v_mul_f32_e32 v15, 0xbfb8aa3b, v15
	v_log_f32_e32 v14, v14
	v_rcp_f32_e32 v16, v16
	v_exp_f32_e32 v15, v15
	s_waitcnt lgkmcnt(2)
	v_lshlrev_b32_e32 v17, 16, v26
	v_fmamk_f32 v28, v14, 0x3f317218, v30
	v_fma_f32 v14, v31, v16, v22
	v_sub_f32_e32 v16, 1.0, v16
	v_add_f32_e32 v15, 1.0, v15
	v_mul_f32_e32 v20, v31, v16
	v_log_f32_e32 v14, v14
	v_rcp_f32_e32 v15, v15
	v_lshlrev_b32_e32 v16, 16, v19
	v_mul_f32_e32 v16, 0xbfb8aa3b, v16
	v_exp_f32_e32 v16, v16
	v_fmamk_f32 v25, v14, 0x3f317218, v28
	v_fma_f32 v14, v31, v15, v22
	v_sub_f32_e32 v15, 1.0, v15
	v_mul_f32_e32 v18, v31, v15
	v_lshlrev_b32_e32 v15, 16, v23
	v_add_f32_e32 v16, 1.0, v16
	v_mul_f32_e32 v15, 0xbfb8aa3b, v15
	v_log_f32_e32 v14, v14
	v_rcp_f32_e32 v16, v16
	v_exp_f32_e32 v15, v15
	v_mul_f32_e32 v17, 0xbfb8aa3b, v17
	v_fmamk_f32 v21, v14, 0x3f317218, v25
	v_fma_f32 v14, v31, v16, v22
	v_add_f32_e32 v15, 1.0, v15
	v_log_f32_e32 v14, v14
	v_rcp_f32_e32 v15, v15
	v_exp_f32_e32 v17, v17
	v_sub_f32_e32 v16, 1.0, v16
	v_fmamk_f32 v19, v14, 0x3f317218, v21
	v_fma_f32 v14, v31, v15, v22
	v_add_f32_e32 v17, 1.0, v17
	v_log_f32_e32 v14, v14
	v_rcp_f32_e32 v23, v17
	v_sub_f32_e32 v15, 1.0, v15
	v_mul_f32_e32 v0, v31, v0
	v_fmamk_f32 v17, v14, 0x3f317218, v19
	v_fma_f32 v26, v31, v23, v22
	v_sub_f32_e32 v14, 1.0, v23
	s_waitcnt lgkmcnt(1)
	v_lshlrev_b32_e32 v23, 16, v29
	v_mul_f32_e32 v23, 0xbfb8aa3b, v23
	s_waitcnt lgkmcnt(0)
	v_lshlrev_b32_e32 v29, 16, v32
	v_exp_f32_e32 v23, v23
	v_mul_f32_e32 v29, 0xbfb8aa3b, v29
	v_exp_f32_e32 v29, v29
	v_log_f32_e32 v26, v26
	v_add_f32_e32 v23, 1.0, v23
	v_rcp_f32_e32 v23, v23
	v_add_f32_e32 v29, 1.0, v29
	v_rcp_f32_e32 v40, v29
	v_fmamk_f32 v29, v26, 0x3f317218, v17
	v_fma_f32 v26, v31, v23, v22
	v_log_f32_e32 v26, v26
	v_fmac_f32_e32 v22, v31, v40
	v_log_f32_e32 v32, v22
	v_sub_f32_e32 v22, 1.0, v23
	v_fmamk_f32 v26, v26, 0x3f317218, v29
	v_sub_f32_e32 v40, 1.0, v40
	v_fmamk_f32 v23, v32, 0x3f317218, v26
	ds_write_b32 v175, v23 offset:52224
	ds_read_u16 v32, v184
	ds_read_u16 v33, v184 offset:272
	ds_read_u16 v34, v184 offset:544
	ds_read_u16 v35, v184 offset:816
	ds_read_u16 v36, v184 offset:1088
	ds_read_u16 v37, v184 offset:1360
	ds_read_u16 v38, v184 offset:1632
	ds_read_u16 v39, v184 offset:1904
	ds_read_u16 v41, v184 offset:2176
	ds_read_u16 v42, v184 offset:2448
	ds_read_u16 v43, v184 offset:2720
	ds_read_u16 v44, v184 offset:2992
	ds_read_u16 v45, v184 offset:3264
	ds_read_u16 v46, v184 offset:3536
	ds_read_u16 v47, v184 offset:3808
	ds_read_u16 v120, v184 offset:4080
	s_waitcnt lgkmcnt(14)
	v_lshl_or_b32 v32, v33, 16, v32
	s_waitcnt lgkmcnt(12)
	v_lshl_or_b32 v33, v35, 16, v34
	s_waitcnt lgkmcnt(10)
	v_lshl_or_b32 v34, v37, 16, v36
	s_waitcnt lgkmcnt(8)
	v_lshl_or_b32 v35, v39, 16, v38
	s_waitcnt lgkmcnt(6)
	v_lshl_or_b32 v36, v42, 16, v41
	v_add_u32_e32 v41, 0x8800, v185
	s_waitcnt lgkmcnt(4)
	v_lshl_or_b32 v37, v44, 16, v43
	s_waitcnt lgkmcnt(2)
	v_lshl_or_b32 v38, v46, 16, v45
	s_waitcnt lgkmcnt(0)
	v_lshl_or_b32 v39, v120, 16, v47
	ds_write2_b64 v41, v[32:33], v[34:35] offset1:1
	v_add_u32_e32 v32, 0x8810, v185
	ds_write2_b64 v32, v[36:37], v[38:39] offset1:1
	ds_read_u16 v32, v186
	ds_read_u16 v33, v186 offset:272
	ds_read_u16 v34, v186 offset:544
	ds_read_u16 v35, v186 offset:816
	ds_read_u16 v36, v186 offset:1088
	ds_read_u16 v37, v186 offset:1360
	ds_read_u16 v39, v186 offset:1632
	ds_read_u16 v42, v186 offset:1904
	s_waitcnt lgkmcnt(6)
	v_lshlrev_b32_e32 v33, 16, v33
	v_lshlrev_b32_e32 v32, 16, v32
	v_mul_f32_e32 v41, 0xbfb8aa3b, v33
	v_mul_f32_e32 v38, 0xbfb8aa3b, v32
	v_exp_f32_e32 v41, v41
	v_exp_f32_e32 v38, v38
	s_waitcnt lgkmcnt(5)
	v_lshlrev_b32_e32 v34, 16, v34
	v_mul_f32_e32 v43, 0xbfb8aa3b, v34
	v_add_f32_e32 v41, 1.0, v41
	v_add_f32_e32 v38, 1.0, v38
	v_rcp_f32_e32 v41, v41
	v_rcp_f32_e32 v38, v38
	s_waitcnt lgkmcnt(3)
	v_lshlrev_b32_e32 v36, 16, v36
	v_exp_f32_e32 v44, v43
	v_mul_f32_e32 v41, v41, v33
	v_lshlrev_b32_e32 v33, 16, v35
	v_mul_f32_e32 v43, v38, v32
	v_mul_f32_e32 v35, 0xbfb8aa3b, v33
	v_mul_f32_e32 v38, 0xbfb8aa3b, v36
	v_exp_f32_e32 v35, v35
	v_exp_f32_e32 v38, v38
	v_add_f32_e32 v32, 1.0, v44
	v_rcp_f32_e32 v32, v32
	v_add_f32_e32 v35, 1.0, v35
	v_add_f32_e32 v38, 1.0, v38
	v_mul_f32_e32 v10, v31, v10
	v_mul_f32_e32 v16, v31, v16
	v_mul_f32_e32 v15, v31, v15
	v_mul_f32_e32 v14, v31, v14
	v_mul_f32_e32 v22, v31, v22
	v_mul_f32_e32 v31, v31, v40
	v_rcp_f32_e32 v35, v35
	v_rcp_f32_e32 v40, v38
	s_waitcnt lgkmcnt(2)
	v_lshlrev_b32_e32 v37, 16, v37
	v_mul_f32_e32 v38, 0xbfb8aa3b, v37
	v_exp_f32_e32 v44, v38
	v_mul_f32_e32 v38, v32, v34
	s_waitcnt lgkmcnt(1)
	v_lshlrev_b32_e32 v34, 16, v39
	v_mul_f32_e32 v35, v35, v33
	v_mul_f32_e32 v33, v40, v36
	v_mul_f32_e32 v36, 0xbfb8aa3b, v34
	s_waitcnt lgkmcnt(0)
	v_lshlrev_b32_e32 v39, 16, v42
	v_exp_f32_e32 v36, v36
	v_mul_f32_e32 v40, 0xbfb8aa3b, v39
	v_exp_f32_e32 v40, v40
	v_add_f32_e32 v32, 1.0, v44
	v_add_f32_e32 v36, 1.0, v36
	v_rcp_f32_e32 v32, v32
	v_rcp_f32_e32 v36, v36
	v_add_f32_e32 v40, 1.0, v40
	v_rcp_f32_e32 v40, v40
	ds_read_u16 v42, v186 offset:2176
	ds_read_u16 v44, v186 offset:2448
	ds_read_u16 v45, v186 offset:2720
	ds_read_u16 v46, v186 offset:2992
	ds_read_u16 v47, v186 offset:3264
	ds_read_u16 v120, v186 offset:3536
	ds_read_u16 v121, v186 offset:3808
	ds_read_u16 v122, v186 offset:4080
	s_waitcnt lgkmcnt(7)
	v_lshlrev_b32_e32 v42, 16, v42
	v_mul_f32_e32 v123, 0xbfb8aa3b, v42
	v_mul_f32_e32 v124, v32, v37
	v_mul_f32_e32 v125, v36, v34
	s_waitcnt lgkmcnt(6)
	v_lshlrev_b32_e32 v34, 16, v44
	s_waitcnt lgkmcnt(5)
	v_lshlrev_b32_e32 v37, 16, v45
	v_exp_f32_e32 v123, v123
	v_mul_f32_e32 v126, v40, v39
	v_mul_f32_e32 v36, 0xbfb8aa3b, v34
	v_mul_f32_e32 v39, 0xbfb8aa3b, v37
	v_exp_f32_e32 v36, v36
	v_exp_f32_e32 v39, v39
	s_waitcnt lgkmcnt(4)
	v_lshlrev_b32_e32 v40, 16, v46
	v_add_f32_e32 v32, 1.0, v123
	v_mul_f32_e32 v44, 0xbfb8aa3b, v40
	v_rcp_f32_e32 v32, v32
	v_add_f32_e32 v36, 1.0, v36
	v_add_f32_e32 v39, 1.0, v39
	v_exp_f32_e32 v45, v44
	v_rcp_f32_e32 v36, v36
	v_rcp_f32_e32 v39, v39
	v_mul_f32_e32 v44, v32, v42
	v_add_f32_e32 v32, 1.0, v45
	s_waitcnt lgkmcnt(2)
	v_lshlrev_b32_e32 v45, 16, v120
	v_mul_f32_e32 v42, v36, v34
	v_mul_f32_e32 v39, v39, v37
	v_lshlrev_b32_e32 v34, 16, v47
	v_mul_f32_e32 v37, 0xbfb8aa3b, v45
	v_mul_f32_e32 v36, 0xbfb8aa3b, v34
	v_exp_f32_e32 v37, v37
	v_exp_f32_e32 v36, v36
	s_waitcnt lgkmcnt(1)
	v_lshlrev_b32_e32 v120, 16, v121
	v_rcp_f32_e32 v32, v32
	v_add_f32_e32 v37, 1.0, v37
	v_add_f32_e32 v36, 1.0, v36
	v_rcp_f32_e32 v46, v37
	v_mul_f32_e32 v37, 0xbfb8aa3b, v120
	v_rcp_f32_e32 v36, v36
	v_exp_f32_e32 v47, v37
	v_mul_f32_e32 v37, v32, v40
	v_mul_f32_e32 v32, v46, v45
	v_mul_f32_e32 v34, v36, v34
	v_add_f32_e32 v36, 1.0, v47
	v_rcp_f32_e32 v36, v36
	s_waitcnt lgkmcnt(0)
	v_lshlrev_b32_e32 v45, 16, v122
	v_mul_f32_e32 v40, 0xbfb8aa3b, v45
	v_exp_f32_e32 v40, v40
	s_barrier
; #define LAS __attribute__((address_space(3)))
; DI bf16_t f2bf(float x) { return (bf16_t)(pk2(x, 0.f) & 0xffffu); }
; DI void hg_phase_c(const P& p, const bf16_t* PROJ, const bf16_t* ST, bf16_t* Y, LAS unsigned char* L, unsigned* qcnt) {
;     ...
;         float off = 0.f;
; #pragma unroll
;         for (int q = 0; q < 4; ++q) { const float v = psum[q * 128 + d]; off += (q < part) ? v : 0.f; }
; #pragma unroll
;         for (int i = 0; i < 16; ++i) { const float g = off + G[i];
;             *(LAS bf16_t*)(qd + (16 * part + i) * 272 + d * 2) = f2bf(qs[i] * __expf(g));
;             *(LAS bf16_t*)(ki + (16 * part + i) * 272 + d * 2) = f2bf(kk[i] * __expf(-g)); }
;         __syncthreads();
	ds_read2st64_b32 v[46:47], v176 offset0:204 offset1:206
	v_mul_f32_e32 v36, v36, v120
	ds_read2st64_b32 v[120:121], v176 offset0:208 offset1:210
	v_add_f32_e32 v40, 1.0, v40
	v_rcp_f32_e32 v122, v40
	s_waitcnt lgkmcnt(1)
	v_add_f32_e32 v40, 0, v46
	v_cndmask_b32_e64 v40, 0, v40, s[8:9]
	v_cndmask_b32_e64 v46, 0, v47, s[10:11]
	v_add_f32_e32 v40, v40, v46
	s_waitcnt lgkmcnt(0)
	v_cndmask_b32_e64 v46, 0, v120, s[12:13]
	v_add_f32_e32 v40, v40, v46
	v_cndmask_b32_e64 v46, 0, v121, s[14:15]
	v_add_f32_e32 v40, v40, v46
	v_add_f32_e32 v46, v11, v40
	v_mul_f32_e32 v11, 0x3fb8aa3b, v46
	v_exp_f32_e32 v47, v11
	v_mul_f32_e32 v11, v122, v45
	v_mul_f32_e32 v45, 0xbfb8aa3b, v46
	v_exp_f32_e32 v45, v45
	v_add_f32_e32 v9, v9, v40
	v_add_f32_e32 v7, v7, v40
	v_add_f32_e32 v5, v5, v40
	v_mul_f32_e32 v8, v8, v45
	v_cvt_pk_bf16_f32 v8, v8, s0
	ds_write_b16 v187, v8 offset:17408
	v_mul_f32_e32 v8, 0xbfb8aa3b, v9
	v_exp_f32_e32 v8, v8
	v_add_f32_e32 v3, v3, v40
	v_mul_f32_e32 v43, v43, v47
	v_cvt_pk_bf16_f32 v43, v43, s0
	v_mul_f32_e32 v6, v6, v8
	v_cvt_pk_bf16_f32 v6, v6, s0
	ds_write_b16 v187, v6 offset:17680
	v_mul_f32_e32 v6, 0xbfb8aa3b, v7
	v_exp_f32_e32 v6, v6
	ds_write_b16 v187, v43
	v_mul_f32_e32 v43, 0x3fb8aa3b, v9
	v_mul_f32_e32 v8, 0x3fb8aa3b, v7
	v_mul_f32_e32 v4, v4, v6
	v_cvt_pk_bf16_f32 v4, v4, s0
	ds_write_b16 v187, v4 offset:17952
	v_mul_f32_e32 v4, 0xbfb8aa3b, v5
	v_exp_f32_e32 v4, v4
	v_mul_f32_e32 v6, 0x3fb8aa3b, v5
	v_exp_f32_e32 v43, v43
	v_exp_f32_e32 v8, v8
	v_mul_f32_e32 v2, v2, v4
	v_cvt_pk_bf16_f32 v2, v2, s0
	v_mul_f32_e32 v4, 0x3fb8aa3b, v3
	v_exp_f32_e32 v4, v4
	ds_write_b16 v187, v2 offset:18224
	v_mul_f32_e32 v2, 0xbfb8aa3b, v3
	v_exp_f32_e32 v2, v2
	v_mul_f32_e32 v3, v33, v4
	v_cvt_pk_bf16_f32 v3, v3, s0
	ds_write_b16 v187, v3 offset:1088
	v_mul_f32_e32 v1, v1, v2
	v_add_f32_e32 v2, v13, v40
	v_cvt_pk_bf16_f32 v1, v1, s0
	v_mul_f32_e32 v3, 0x3fb8aa3b, v2
	v_exp_f32_e32 v3, v3
	ds_write_b16 v187, v1 offset:18496
	v_mul_f32_e32 v1, 0xbfb8aa3b, v2
	v_exp_f32_e32 v1, v1
	v_mul_f32_e32 v2, v124, v3
	v_cvt_pk_bf16_f32 v2, v2, s0
	ds_write_b16 v187, v2 offset:1360
	v_mul_f32_e32 v0, v0, v1
	v_add_f32_e32 v1, v12, v40
	v_mul_f32_e32 v2, 0x3fb8aa3b, v1
	v_exp_f32_e32 v2, v2
	v_cvt_pk_bf16_f32 v0, v0, s0
	ds_write_b16 v187, v0 offset:18768
	v_mul_f32_e32 v0, 0xbfb8aa3b, v1
	v_mul_f32_e32 v1, v125, v2
	v_cvt_pk_bf16_f32 v1, v1, s0
	v_exp_f32_e32 v0, v0
	ds_write_b16 v187, v1 offset:1632
	v_add_f32_e32 v1, v30, v40
	v_mul_f32_e32 v2, 0x3fb8aa3b, v1
	v_exp_f32_e32 v2, v2
	v_mul_f32_e32 v0, v10, v0
	v_cvt_pk_bf16_f32 v0, v0, s0
	ds_write_b16 v187, v0 offset:19040
	v_mul_f32_e32 v0, 0xbfb8aa3b, v1
	v_mul_f32_e32 v1, v126, v2
	v_cvt_pk_bf16_f32 v1, v1, s0
	v_exp_f32_e32 v0, v0
	ds_write_b16 v187, v1 offset:1904
	v_add_f32_e32 v1, v28, v40
	v_mul_f32_e32 v2, 0x3fb8aa3b, v1
	v_exp_f32_e32 v2, v2
	v_mul_f32_e32 v0, v27, v0
	v_cvt_pk_bf16_f32 v0, v0, s0
	ds_write_b16 v187, v0 offset:19312
	v_mul_f32_e32 v0, 0xbfb8aa3b, v1
	v_mul_f32_e32 v1, v44, v2
	v_cvt_pk_bf16_f32 v1, v1, s0
	v_exp_f32_e32 v0, v0
	ds_write_b16 v187, v1 offset:2176
	v_add_f32_e32 v1, v25, v40
	v_mul_f32_e32 v2, 0x3fb8aa3b, v1
	v_exp_f32_e32 v2, v2
	v_mul_f32_e32 v0, v24, v0
	v_cvt_pk_bf16_f32 v0, v0, s0
	ds_write_b16 v187, v0 offset:19584
	v_mul_f32_e32 v0, 0xbfb8aa3b, v1
	v_mul_f32_e32 v1, v42, v2
	v_cvt_pk_bf16_f32 v1, v1, s0
	v_exp_f32_e32 v0, v0
	ds_write_b16 v187, v1 offset:2448
	v_add_f32_e32 v1, v21, v40
	v_mul_f32_e32 v2, 0x3fb8aa3b, v1
	v_exp_f32_e32 v2, v2
	v_mul_f32_e32 v0, v20, v0
	v_cvt_pk_bf16_f32 v0, v0, s0
	ds_write_b16 v187, v0 offset:19856
	v_mul_f32_e32 v0, 0xbfb8aa3b, v1
	v_mul_f32_e32 v1, v39, v2
	v_exp_f32_e32 v0, v0
	v_cvt_pk_bf16_f32 v1, v1, s0
	ds_write_b16 v187, v1 offset:2720
	v_add_f32_e32 v1, v19, v40
	v_mul_f32_e32 v2, 0x3fb8aa3b, v1
	v_exp_f32_e32 v2, v2
	v_mul_f32_e32 v0, v18, v0
	v_cvt_pk_bf16_f32 v0, v0, s0
	ds_write_b16 v187, v0 offset:20128
	v_mul_f32_e32 v0, 0xbfb8aa3b, v1
	v_exp_f32_e32 v0, v0
	v_mul_f32_e32 v1, v37, v2
	v_cvt_pk_bf16_f32 v1, v1, s0
	ds_write_b16 v187, v1 offset:2992
	v_add_f32_e32 v1, v17, v40
	v_mul_f32_e32 v2, 0x3fb8aa3b, v1
	v_mul_f32_e32 v0, v16, v0
	v_exp_f32_e32 v2, v2
	v_cvt_pk_bf16_f32 v0, v0, s0
	ds_write_b16 v187, v0 offset:20400
	v_mul_f32_e32 v0, 0xbfb8aa3b, v1
	v_exp_f32_e32 v0, v0
	v_mul_f32_e32 v1, v34, v2
	v_cvt_pk_bf16_f32 v1, v1, s0
	ds_write_b16 v187, v1 offset:3264
	v_add_f32_e32 v1, v29, v40
	v_mul_f32_e32 v0, v15, v0
	v_mul_f32_e32 v2, 0x3fb8aa3b, v1
	v_cvt_pk_bf16_f32 v0, v0, s0
	v_exp_f32_e32 v2, v2
	ds_write_b16 v187, v0 offset:20672
	v_mul_f32_e32 v0, 0xbfb8aa3b, v1
	v_exp_f32_e32 v0, v0
	v_mul_f32_e32 v1, v32, v2
	v_cvt_pk_bf16_f32 v1, v1, s0
	ds_write_b16 v187, v1 offset:3536
	v_mul_f32_e32 v0, v14, v0
	v_add_f32_e32 v1, v26, v40
	v_cvt_pk_bf16_f32 v0, v0, s0
	v_mul_f32_e32 v2, 0x3fb8aa3b, v1
	v_exp_f32_e32 v2, v2
	ds_write_b16 v187, v0 offset:20944
	v_mul_f32_e32 v0, 0xbfb8aa3b, v1
	v_exp_f32_e32 v0, v0
	v_mul_f32_e32 v1, v36, v2
	v_cvt_pk_bf16_f32 v1, v1, s0
	ds_write_b16 v187, v1 offset:3808
	v_mul_f32_e32 v0, v22, v0
	v_cvt_pk_bf16_f32 v0, v0, s0
	v_add_f32_e32 v1, v23, v40
	v_mul_f32_e32 v2, 0x3fb8aa3b, v1
	ds_write_b16 v187, v0 offset:21216
	v_mul_f32_e32 v0, 0xbfb8aa3b, v1
	v_exp_f32_e32 v6, v6
	v_exp_f32_e32 v2, v2
	v_exp_f32_e32 v0, v0
	v_mul_f32_e32 v9, v41, v43
	v_mul_f32_e32 v7, v38, v8
	v_mul_f32_e32 v5, v35, v6
	v_mul_f32_e32 v1, v11, v2
	v_mul_f32_e32 v0, v31, v0
	v_cvt_pk_bf16_f32 v9, v9, s0
	v_cvt_pk_bf16_f32 v7, v7, s0
	v_cvt_pk_bf16_f32 v5, v5, s0
	v_cvt_pk_bf16_f32 v1, v1, s0
	v_cvt_pk_bf16_f32 v0, v0, s0
	ds_write_b16 v187, v9 offset:272
	ds_write_b16 v187, v7 offset:544
	ds_write_b16 v187, v5 offset:816
	ds_write_b16 v187, v1 offset:4080
	ds_write_b16 v187, v0 offset:21488
	s_waitcnt lgkmcnt(0)
	s_barrier
; #define LAS __attribute__((address_space(3)))
; #define MFMA32(a, b, c) __builtin_amdgcn_mfma_f32_32x32x16_bf16((a), (b), (c), 0, 0, 0)
; DI int crow(int reg, int h) { return (reg & 3) + 8 * (reg >> 2) + 4 * h; }
; DI void hg_phase_c(const P& p, const bf16_t* PROJ, const bf16_t* ST, bf16_t* Y, LAS unsigned char* L, unsigned* qcnt) {
;     ...
;         bf16x8 qfr[8];
; #pragma unroll
;         for (int ks = 0; ks < 8; ++ks) qfr[ks] = *(const LAS bf16x8*)(qd + (32 * tt + r) * 272 + (16 * ks + 8 * lh) * 2);
;         f32x16 O = zero16();
; #pragma unroll
;         for (int st = 0; st < 2; ++st) {
;             if (st <= tt) {
;                 f32x16 X = zero16();
; #pragma unroll
;                 for (int ks = 0; ks < 8; ++ks) { const bf16x8 a = *(const LAS bf16x8*)(ki + (32 * st + r) * 272 + (16 * ks + 8 * lh) * 2); X = MFMA32(a, qfr[ks], X); }
;                 if (st == tt) {
; #pragma unroll
;                     for (int reg = 0; reg < 16; ++reg) X[reg] = (crow(reg, lh) > r) ? 0.f : X[reg];
;                 }
	ds_read_b128 v[148:151], v188
	ds_read_b128 v[144:147], v188 offset:32
	ds_read_b128 v[140:143], v188 offset:64
	ds_read_b128 v[136:139], v188 offset:96
	ds_read_b128 v[132:135], v188 offset:128
	ds_read_b128 v[128:131], v188 offset:160
	ds_read_b128 v[124:127], v188 offset:192
	ds_read_b128 v[120:123], v188 offset:224
	s_cbranch_vccnz .LBB0_434
	ds_read_b128 v[0:3], v190 offset:17408
	ds_read_b128 v[16:19], v190 offset:17440
	s_andn2_b64 vcc, exec, s[68:69]
	s_waitcnt lgkmcnt(1)
	v_mfma_f32_32x32x16_bf16 v[0:15], v[0:3], v[148:151], 0
	s_waitcnt lgkmcnt(0)
	v_mfma_f32_32x32x16_bf16 v[0:15], v[16:19], v[144:147], v[0:15]
	ds_read_b128 v[16:19], v190 offset:17472
	ds_read_b128 v[20:23], v190 offset:17504
	s_waitcnt lgkmcnt(1)
	v_mfma_f32_32x32x16_bf16 v[0:15], v[16:19], v[140:143], v[0:15]
	s_waitcnt lgkmcnt(0)
	v_mfma_f32_32x32x16_bf16 v[0:15], v[20:23], v[136:139], v[0:15]
	ds_read_b128 v[16:19], v190 offset:17536
	ds_read_b128 v[20:23], v190 offset:17568
	s_waitcnt lgkmcnt(1)
	v_mfma_f32_32x32x16_bf16 v[0:15], v[16:19], v[132:135], v[0:15]
	s_waitcnt lgkmcnt(0)
	v_mfma_f32_32x32x16_bf16 v[0:15], v[20:23], v[128:131], v[0:15]
	ds_read_b128 v[16:19], v190 offset:17600
	ds_read_b128 v[20:23], v190 offset:17632
	s_waitcnt lgkmcnt(1)
	v_mfma_f32_32x32x16_bf16 v[0:15], v[16:19], v[124:127], v[0:15]
	s_waitcnt lgkmcnt(0)
	v_mfma_f32_32x32x16_bf16 v[0:15], v[20:23], v[120:123], v[0:15]
	s_cbranch_vccnz .LBB0_433
	s_nop 10
	v_cndmask_b32_e64 v0, v0, 0, s[16:17]
	v_cndmask_b32_e64 v1, 0, v1, s[18:19]
	v_cndmask_b32_e64 v2, v2, 0, s[20:21]
	v_cndmask_b32_e64 v3, v3, 0, s[22:23]
	v_cndmask_b32_e64 v4, v4, 0, s[24:25]
	v_cndmask_b32_e64 v5, v5, 0, s[26:27]
	v_cndmask_b32_e64 v6, v6, 0, s[28:29]
	v_cndmask_b32_e64 v7, v7, 0, s[30:31]
	v_cndmask_b32_e64 v8, v8, 0, s[34:35]
	v_cndmask_b32_e64 v9, v9, 0, s[36:37]
	v_cndmask_b32_e64 v10, v10, 0, s[38:39]
	v_cndmask_b32_e64 v11, v11, 0, s[40:41]
	v_cndmask_b32_e64 v12, v12, 0, s[42:43]
	v_cndmask_b32_e64 v13, v13, 0, s[44:45]
	v_cndmask_b32_e64 v14, v14, 0, s[46:47]
	v_cndmask_b32_e64 v15, v15, 0, s[48:49]
